# dil_attn Q/K/V loads as plain cached loads (coherence provided by the grid barrier acquire, as for the GEMM operand loads)
# speedup vs baseline: 1.0021x; 1.0021x over previous
.LBB0_112:
	v_lshlrev_b32_e32 v0, s46, v194
	v_add3_u32 v191, v193, s33, v0
	v_lshrrev_b32_e32 v0, 1, v191
	v_and_b32_e32 v0, 0x7ffff0, v0
	v_or_b32_e32 v0, s41, v0
	v_add_u32_e32 v244, v193, v111
	v_lshl_or_b32 v176, v0, 9, v189
	v_subrev_u32_e32 v192, 64, v191
	v_lshl_add_u64 v[4:5], v[176:177], 1, s[38:39]
	v_add_u32_e32 v245, v192, v112
	v_add_u32_e32 v246, v191, v103
	global_load_dwordx4 v[228:231], v[4:5], off
	global_load_dwordx4 v[232:235], v[4:5], off offset:1024
	global_load_dwordx4 v[236:239], v[4:5], off offset:2048
	global_load_dwordx4 v[240:243], v[4:5], off offset:3072
	s_movk_i32 s18, 0x1f0
	v_cmp_lt_i32_e32 vcc, -1, v244
	v_cmp_gt_i32_e64 s[16:17], s45, v244
	s_and_b64 vcc, vcc, s[16:17]
	v_cndmask_b32_e32 v6, v246, v245, vcc
	v_lshrrev_b32_e32 v7, 1, v6
	v_and_b32_e32 v7, 0x7ffff0, v7
	v_lshlrev_b32_e32 v6, 4, v6
	v_or_b32_e32 v7, s41, v7
	v_and_or_b32 v6, v6, s18, v113
	v_lshl_add_u32 v176, v7, 9, v6
	v_lshl_add_u64 v[4:5], v[176:177], 1, s[38:39]
	global_load_dwordx4 v[118:121], v[4:5], off
	global_load_dwordx4 v[122:125], v[4:5], off offset:1024
	global_load_dwordx4 v[126:129], v[4:5], off offset:2048
	global_load_dwordx4 v[130:133], v[4:5], off offset:3072
	v_add_u32_e32 v6, 32, v244
	v_cmp_lt_i32_e32 vcc, -1, v6
	v_cmp_gt_i32_e64 s[16:17], s45, v6
	v_add_u32_e32 v7, 32, v245
	s_and_b64 vcc, vcc, s[16:17]
	v_cndmask_b32_e32 v6, v246, v7, vcc
	v_lshrrev_b32_e32 v7, 1, v6
	v_and_b32_e32 v7, 0x7ffff0, v7
	v_lshlrev_b32_e32 v6, 4, v6
	v_or_b32_e32 v7, s41, v7
	v_and_or_b32 v6, v6, s18, v113
	v_lshl_add_u32 v176, v7, 9, v6
	v_lshl_add_u64 v[4:5], v[176:177], 1, s[38:39]
	global_load_dwordx4 v[134:137], v[4:5], off
	global_load_dwordx4 v[138:141], v[4:5], off offset:1024
	global_load_dwordx4 v[142:145], v[4:5], off offset:2048
	global_load_dwordx4 v[146:149], v[4:5], off offset:3072
	v_add_u32_e32 v6, 64, v244
	v_cmp_lt_i32_e32 vcc, -1, v6
	v_cmp_gt_i32_e64 s[16:17], s45, v6
	v_add_u32_e32 v7, 64, v245
	s_and_b64 vcc, vcc, s[16:17]
	v_cndmask_b32_e32 v6, v246, v7, vcc
	v_lshrrev_b32_e32 v7, 1, v6
	v_and_b32_e32 v7, 0x7ffff0, v7
	v_lshlrev_b32_e32 v6, 4, v6
	v_or_b32_e32 v7, s41, v7
	v_and_or_b32 v6, v6, s18, v113
	v_lshl_add_u32 v176, v7, 9, v6
	v_lshl_add_u64 v[4:5], v[176:177], 1, s[38:39]
	global_load_dwordx4 v[150:153], v[4:5], off
	global_load_dwordx4 v[154:157], v[4:5], off offset:1024
	global_load_dwordx4 v[158:161], v[4:5], off offset:2048
	global_load_dwordx4 v[162:165], v[4:5], off offset:3072
	v_add_u32_e32 v6, 96, v244
	v_cmp_lt_i32_e32 vcc, -1, v6
	v_cmp_gt_i32_e64 s[16:17], s45, v6
	v_add_u32_e32 v7, 96, v245
	s_and_b64 vcc, vcc, s[16:17]
	v_cndmask_b32_e32 v6, v246, v7, vcc
	v_lshrrev_b32_e32 v7, 1, v6
	v_and_b32_e32 v7, 0x7ffff0, v7
	v_lshlrev_b32_e32 v6, 4, v6
	v_or_b32_e32 v7, s41, v7
	v_and_or_b32 v6, v6, s18, v113
	v_lshl_add_u32 v176, v7, 9, v6
	v_lshl_add_u64 v[4:5], v[176:177], 1, s[38:39]
	global_load_dwordx4 v[166:169], v[4:5], off
	global_load_dwordx4 v[170:173], v[4:5], off offset:1024
	global_load_dwordx4 v[180:183], v[4:5], off offset:2048
	global_load_dwordx4 v[184:187], v[4:5], off offset:3072
	v_add_u32_e32 v6, 128, v244
	v_cmp_lt_i32_e32 vcc, -1, v6
	v_cmp_gt_i32_e64 s[16:17], s45, v6
	v_add_u32_e32 v7, 128, v245
	s_and_b64 vcc, vcc, s[16:17]
	v_cndmask_b32_e32 v6, v246, v7, vcc
	v_lshrrev_b32_e32 v7, 1, v6
	v_and_b32_e32 v7, 0x7ffff0, v7
	v_lshlrev_b32_e32 v6, 4, v6
	v_or_b32_e32 v7, s41, v7
	v_and_or_b32 v6, v6, s18, v113
	v_lshl_add_u32 v176, v7, 9, v6
	v_lshl_add_u64 v[4:5], v[176:177], 1, s[38:39]
	global_load_dwordx4 v[196:199], v[4:5], off
	global_load_dwordx4 v[214:217], v[4:5], off offset:1024
	global_load_dwordx4 v[218:221], v[4:5], off offset:2048
	global_load_dwordx4 v[222:225], v[4:5], off offset:3072
	v_add_u32_e32 v192, v192, v100
	v_cmp_lt_i32_e32 vcc, 63, v193
	v_cmp_gt_i32_e64 s[16:17], s47, v193
	s_and_b64 s[16:17], vcc, s[16:17]
	v_cmp_lt_i32_e32 vcc, 47, v193
	v_cmp_gt_i32_e64 s[18:19], s48, v193
	s_and_b64 vcc, vcc, s[18:19]
	s_movk_i32 s20, 0xe000
	v_cndmask_b32_e64 v6, v191, v192, s[16:17]
	v_add_u32_e32 v8, 16, v192
	v_lshlrev_b32_e32 v7, 8, v6
	v_and_b32_e32 v6, 31, v6
	v_cndmask_b32_e32 v8, v191, v8, vcc
	v_and_or_b32 v6, v7, s20, v6
	v_or_b32_e32 v176, v6, v190
	v_lshl_add_u64 v[4:5], v[176:177], 1, s[2:3]
	global_load_dwordx4 v[88:91], v[4:5], off
	global_load_dwordx4 v[92:95], v[4:5], off offset:2048
	v_lshlrev_b32_e32 v7, 8, v8
	v_and_b32_e32 v8, 31, v8
	v_and_or_b32 v8, v7, s20, v8
	v_or_b32_e32 v176, v8, v190
	v_lshl_add_u64 v[4:5], v[176:177], 1, s[2:3]
	global_load_dwordx4 v[80:83], v[4:5], off
	global_load_dwordx4 v[84:87], v[4:5], off offset:2048
	v_readlane_b32 s18, v249, 26
	v_readlane_b32 s19, v249, 27
	s_waitcnt vmcnt(20)
	v_mfma_f32_32x32x16_bf16 v[64:79], v[118:121], v[228:231], 0
	v_mfma_f32_32x32x16_bf16 v[64:79], v[122:125], v[232:235], v[64:79]
	v_mfma_f32_32x32x16_bf16 v[64:79], v[126:129], v[236:239], v[64:79]
	v_mfma_f32_32x32x16_bf16 v[64:79], v[130:133], v[240:243], v[64:79]
	s_waitcnt vmcnt(16)
	v_mfma_f32_32x32x16_bf16 v[48:63], v[134:137], v[228:231], 0
	v_mfma_f32_32x32x16_bf16 v[48:63], v[138:141], v[232:235], v[48:63]
	v_mfma_f32_32x32x16_bf16 v[48:63], v[142:145], v[236:239], v[48:63]
	v_mfma_f32_32x32x16_bf16 v[48:63], v[146:149], v[240:243], v[48:63]
	s_waitcnt vmcnt(12)
	v_mfma_f32_32x32x16_bf16 v[32:47], v[150:153], v[228:231], 0
	v_mfma_f32_32x32x16_bf16 v[32:47], v[154:157], v[232:235], v[32:47]
	v_mfma_f32_32x32x16_bf16 v[32:47], v[158:161], v[236:239], v[32:47]
	v_mfma_f32_32x32x16_bf16 v[32:47], v[162:165], v[240:243], v[32:47]
	s_waitcnt vmcnt(8)
	v_mfma_f32_32x32x16_bf16 v[16:31], v[166:169], v[228:231], 0
	v_mfma_f32_32x32x16_bf16 v[16:31], v[170:173], v[232:235], v[16:31]
	v_mfma_f32_32x32x16_bf16 v[16:31], v[180:183], v[236:239], v[16:31]
	v_mfma_f32_32x32x16_bf16 v[16:31], v[184:187], v[240:243], v[16:31]
	s_waitcnt vmcnt(4)
	v_mfma_f32_32x32x16_bf16 v[0:15], v[196:199], v[228:231], 0
	v_mfma_f32_32x32x16_bf16 v[0:15], v[214:217], v[232:235], v[0:15]
	v_mfma_f32_32x32x16_bf16 v[0:15], v[218:221], v[236:239], v[0:15]
	v_mfma_f32_32x32x16_bf16 v[0:15], v[222:225], v[240:243], v[0:15]
	s_movk_i32 s24, 0xe000
	v_cmp_lt_i32_e64 s[20:21], 31, v193
	v_cmp_gt_i32_e64 s[22:23], s49, v193
	v_add_u32_e32 v188, 32, v192
	s_and_b64 s[20:21], s[20:21], s[22:23]
	v_cndmask_b32_e64 v188, v191, v188, s[20:21]
	v_lshlrev_b32_e32 v239, 8, v188
	v_and_b32_e32 v188, 31, v188
	v_and_or_b32 v188, v239, s24, v188
	v_or_b32_e32 v176, v188, v190
	v_lshl_add_u64 v[174:175], v[176:177], 1, s[2:3]
	global_load_dwordx4 v[118:121], v[174:175], off
	global_load_dwordx4 v[122:125], v[174:175], off offset:2048
	v_cmp_lt_i32_e64 s[20:21], 15, v193
	v_cmp_gt_i32_e64 s[22:23], s50, v193
	v_add_u32_e32 v188, 48, v192
	s_and_b64 s[20:21], s[20:21], s[22:23]
	v_cndmask_b32_e64 v188, v191, v188, s[20:21]
	v_lshlrev_b32_e32 v239, 8, v188
	v_and_b32_e32 v188, 31, v188
	v_and_or_b32 v188, v239, s24, v188
	v_or_b32_e32 v176, v188, v190
	v_lshl_add_u64 v[174:175], v[176:177], 1, s[2:3]
	global_load_dwordx4 v[126:129], v[174:175], off
	global_load_dwordx4 v[130:133], v[174:175], off offset:2048
	v_cmp_lt_i32_e64 s[20:21], -1, v193
	v_cmp_gt_i32_e64 s[22:23], s45, v193
	v_add_u32_e32 v188, 64, v192
	s_and_b64 s[20:21], s[20:21], s[22:23]
	v_cndmask_b32_e64 v188, v191, v188, s[20:21]
	v_lshlrev_b32_e32 v239, 8, v188
	v_and_b32_e32 v188, 31, v188
	v_and_or_b32 v188, v239, s24, v188
	v_or_b32_e32 v176, v188, v190
	v_lshl_add_u64 v[174:175], v[176:177], 1, s[2:3]
	global_load_dwordx4 v[134:137], v[174:175], off
	global_load_dwordx4 v[138:141], v[174:175], off offset:2048
	s_movk_i32 s25, 0xffef
	v_cmp_lt_i32_e64 s[20:21], s25, v193
	v_cmp_gt_i32_e64 s[22:23], s51, v193
	v_add_u32_e32 v188, 80, v192
	s_and_b64 s[20:21], s[20:21], s[22:23]
	v_cndmask_b32_e64 v188, v191, v188, s[20:21]
	v_lshlrev_b32_e32 v239, 8, v188
	v_and_b32_e32 v188, 31, v188
	v_and_or_b32 v188, v239, s24, v188
	v_or_b32_e32 v176, v188, v190
	v_lshl_add_u64 v[174:175], v[176:177], 1, s[2:3]
	global_load_dwordx4 v[142:145], v[174:175], off
	global_load_dwordx4 v[146:149], v[174:175], off offset:2048
	s_movk_i32 s25, 0xffdf
	v_cmp_lt_i32_e64 s[20:21], s25, v193
	v_cmp_gt_i32_e64 s[22:23], s52, v193
	v_add_u32_e32 v188, 96, v192
	s_and_b64 s[20:21], s[20:21], s[22:23]
	v_cndmask_b32_e64 v188, v191, v188, s[20:21]
	v_lshlrev_b32_e32 v239, 8, v188
	v_and_b32_e32 v188, 31, v188
	v_and_or_b32 v188, v239, s24, v188
	v_or_b32_e32 v176, v188, v190
	v_lshl_add_u64 v[174:175], v[176:177], 1, s[2:3]
	global_load_dwordx4 v[150:153], v[174:175], off
	global_load_dwordx4 v[154:157], v[174:175], off offset:2048
	s_movk_i32 s25, 0xffcf
	v_cmp_lt_i32_e64 s[20:21], s25, v193
	v_cmp_gt_i32_e64 s[22:23], s53, v193
	v_add_u32_e32 v188, 112, v192
	s_and_b64 s[20:21], s[20:21], s[22:23]
	v_cndmask_b32_e64 v188, v191, v188, s[20:21]
	v_lshlrev_b32_e32 v239, 8, v188
	v_and_b32_e32 v188, 31, v188
	v_and_or_b32 v188, v239, s24, v188
	v_or_b32_e32 v176, v188, v190
	v_lshl_add_u64 v[174:175], v[176:177], 1, s[2:3]
	global_load_dwordx4 v[158:161], v[174:175], off
	global_load_dwordx4 v[162:165], v[174:175], off offset:2048
	s_movk_i32 s25, 0xffbf
	v_cmp_lt_i32_e64 s[20:21], s25, v193
	v_cmp_gt_i32_e64 s[22:23], s54, v193
	v_add_u32_e32 v188, 128, v192
	s_and_b64 s[20:21], s[20:21], s[22:23]
	v_cndmask_b32_e64 v188, v191, v188, s[20:21]
	v_lshlrev_b32_e32 v239, 8, v188
	v_and_b32_e32 v188, 31, v188
	v_and_or_b32 v188, v239, s24, v188
	v_or_b32_e32 v176, v188, v190
	v_lshl_add_u64 v[174:175], v[176:177], 1, s[2:3]
	global_load_dwordx4 v[166:169], v[174:175], off
	global_load_dwordx4 v[170:173], v[174:175], off offset:2048
	s_movk_i32 s25, 0xffaf
	v_cmp_lt_i32_e64 s[20:21], s25, v193
	v_cmp_gt_i32_e64 s[22:23], s55, v193
	v_add_u32_e32 v188, 144, v192
	s_and_b64 s[20:21], s[20:21], s[22:23]
	v_cndmask_b32_e64 v188, v191, v188, s[20:21]
	v_lshlrev_b32_e32 v239, 8, v188
	v_and_b32_e32 v188, 31, v188
	v_and_or_b32 v188, v239, s24, v188
	v_or_b32_e32 v176, v188, v190
	v_lshl_add_u64 v[174:175], v[176:177], 1, s[2:3]
	global_load_dwordx4 v[180:183], v[174:175], off
	global_load_dwordx4 v[184:187], v[174:175], off offset:2048
	v_mov_b32_e32 v254, 0xf149f2ca
	ds_read_b32 v213, v117 offset:640
	ds_read_b32 v214, v117 offset:644
	ds_read_b32 v215, v117 offset:648
	ds_read_b32 v216, v117 offset:652
	ds_read_b32 v217, v117 offset:656
	ds_read_b32 v218, v117 offset:660
	ds_read_b32 v219, v117 offset:664
	ds_read_b32 v220, v117 offset:668
	ds_read_b32 v221, v117 offset:704
	ds_read_b32 v222, v117 offset:708
	ds_read_b32 v223, v117 offset:712
	ds_read_b32 v224, v117 offset:716
	ds_read_b32 v225, v117 offset:720
	ds_read_b32 v226, v117 offset:724
	ds_read_b32 v227, v117 offset:728
	s_and_b64 s[20:21], s[16:17], s[18:19]
	s_waitcnt lgkmcnt(10)
	v_add_f32_e32 v213, v64, v213
	v_cndmask_b32_e64 v97, v254, v213, s[20:21]
	v_readlane_b32 s18, v249, 21
	v_readlane_b32 s19, v249, 22
	s_and_b64 s[20:21], s[16:17], s[18:19]
	v_add_f32_e32 v214, v65, v214
	v_cndmask_b32_e64 v96, v254, v214, s[20:21]
	v_readlane_b32 s18, v249, 18
	v_readlane_b32 s19, v249, 19
	s_and_b64 s[20:21], s[16:17], s[18:19]
	v_add_f32_e32 v215, v66, v215
	v_cndmask_b32_e64 v65, v254, v215, s[20:21]
	v_readlane_b32 s18, v249, 30
	v_readlane_b32 s19, v249, 31
	s_and_b64 s[20:21], s[16:17], s[18:19]
	v_add_f32_e32 v216, v67, v216
	v_cndmask_b32_e64 v64, v254, v216, s[20:21]
	v_readlane_b32 s18, v249, 38
	v_readlane_b32 s19, v249, 39
	s_and_b64 s[20:21], s[16:17], s[18:19]
	v_add_f32_e32 v217, v68, v217
	v_cndmask_b32_e64 v67, v254, v217, s[20:21]
	ds_read_b32 v213, v117 offset:732
	ds_read_b32 v214, v117 offset:768
	ds_read_b32 v215, v117 offset:772
	ds_read_b32 v216, v117 offset:776
	ds_read_b32 v217, v117 offset:780
	v_readlane_b32 s18, v249, 33
	v_readlane_b32 s19, v249, 34
	s_and_b64 s[20:21], s[16:17], s[18:19]
	s_waitcnt lgkmcnt(10)
	v_add_f32_e32 v218, v69, v218
	v_cndmask_b32_e64 v66, v254, v218, s[20:21]
	s_and_b64 s[20:21], s[16:17], s[56:57]
	v_add_f32_e32 v219, v70, v219
	v_cndmask_b32_e64 v69, v254, v219, s[20:21]
	s_and_b64 s[18:19], s[16:17], s[58:59]
	v_add_f32_e32 v220, v71, v220
	v_cndmask_b32_e64 v68, v254, v220, s[18:19]
	s_and_b64 s[18:19], vcc, s[60:61]
	v_add_f32_e32 v221, v72, v221
	v_cndmask_b32_e64 v71, v254, v221, s[18:19]
	s_and_b64 s[18:19], vcc, s[62:63]
	v_add_f32_e32 v222, v73, v222
	v_cndmask_b32_e64 v70, v254, v222, s[18:19]
	ds_read_b32 v218, v117 offset:784
	ds_read_b32 v219, v117 offset:788
	ds_read_b32 v220, v117 offset:792
	ds_read_b32 v221, v117 offset:796
	ds_read_b32 v222, v117 offset:832
	s_and_b64 s[18:19], vcc, s[64:65]
	s_waitcnt lgkmcnt(10)
	v_add_f32_e32 v223, v74, v223
	v_cndmask_b32_e64 v73, v254, v223, s[18:19]
	s_and_b64 s[18:19], vcc, s[66:67]
	v_add_f32_e32 v224, v75, v224
	v_cndmask_b32_e64 v72, v254, v224, s[18:19]
	s_and_b64 s[18:19], vcc, s[68:69]
	v_add_f32_e32 v225, v76, v225
	v_cndmask_b32_e64 v75, v254, v225, s[18:19]
	s_and_b64 s[18:19], vcc, s[70:71]
	v_add_f32_e32 v226, v77, v226
	v_cndmask_b32_e64 v74, v254, v226, s[18:19]
	s_and_b64 s[18:19], vcc, s[72:73]
	v_add_f32_e32 v227, v78, v227
	v_cndmask_b32_e64 v77, v254, v227, s[18:19]
	ds_read_b32 v223, v117 offset:836
	ds_read_b32 v224, v117 offset:840
	ds_read_b32 v225, v117 offset:844
	ds_read_b32 v226, v117 offset:848
	ds_read_b32 v227, v117 offset:852
	s_and_b64 s[18:19], vcc, s[74:75]
	s_waitcnt lgkmcnt(10)
	v_add_f32_e32 v213, v79, v213
	v_cndmask_b32_e64 v76, v254, v213, s[18:19]
	v_cmp_lt_i32_e32 vcc, 31, v193
	v_cmp_gt_i32_e64 s[16:17], s49, v193
	s_and_b64 s[18:19], vcc, s[16:17]
	v_add_f32_e32 v214, v48, v214
	v_cndmask_b32_e64 v79, v254, v214, s[18:19]
	v_add_f32_e32 v215, v49, v215
	v_cndmask_b32_e64 v78, v254, v215, s[18:19]
	v_add_f32_e32 v216, v50, v216
	v_cndmask_b32_e64 v49, v254, v216, s[18:19]
	v_add_f32_e32 v217, v51, v217
	v_cndmask_b32_e64 v48, v254, v217, s[18:19]
	ds_read_b32 v213, v117 offset:856
	ds_read_b32 v214, v117 offset:860
	ds_read_b32 v215, v117 offset:896
	ds_read_b32 v216, v117 offset:900
	ds_read_b32 v217, v117 offset:904
	s_waitcnt lgkmcnt(10)
	v_add_f32_e32 v218, v52, v218
	v_cndmask_b32_e64 v51, v254, v218, s[18:19]
	v_add_f32_e32 v219, v53, v219
	v_cndmask_b32_e64 v50, v254, v219, s[18:19]
	v_add_f32_e32 v220, v54, v220
	v_cndmask_b32_e64 v53, v254, v220, s[18:19]
	v_add_f32_e32 v221, v55, v221
	v_cndmask_b32_e64 v52, v254, v221, s[18:19]
	v_cmp_lt_i32_e32 vcc, 15, v193
	v_cmp_gt_i32_e64 s[16:17], s50, v193
	s_and_b64 s[28:29], vcc, s[16:17]
	v_add_f32_e32 v222, v56, v222
	v_cndmask_b32_e64 v55, v254, v222, s[28:29]
	ds_read_b32 v218, v117 offset:908
	ds_read_b32 v219, v117 offset:912
	ds_read_b32 v220, v117 offset:916
	ds_read_b32 v221, v117 offset:920
	ds_read_b32 v222, v117 offset:924
	s_waitcnt lgkmcnt(10)
	v_add_f32_e32 v223, v57, v223
	v_cndmask_b32_e64 v54, v254, v223, s[28:29]
	v_add_f32_e32 v224, v58, v224
	v_cndmask_b32_e64 v57, v254, v224, s[28:29]
	v_add_f32_e32 v225, v59, v225
	v_cndmask_b32_e64 v56, v254, v225, s[28:29]
	v_add_f32_e32 v226, v60, v226
	v_cndmask_b32_e64 v59, v254, v226, s[28:29]
	v_add_f32_e32 v227, v61, v227
	v_cndmask_b32_e64 v58, v254, v227, s[28:29]
	ds_read_b32 v223, v117 offset:960
	ds_read_b32 v224, v117 offset:964
	ds_read_b32 v225, v117 offset:968
	ds_read_b32 v226, v117 offset:972
	ds_read_b32 v227, v117 offset:976
	s_waitcnt lgkmcnt(10)
	v_add_f32_e32 v213, v62, v213
	v_cndmask_b32_e64 v61, v254, v213, s[28:29]
	v_add_f32_e32 v214, v63, v214
	v_cndmask_b32_e64 v60, v254, v214, s[28:29]
	v_cmp_lt_i32_e32 vcc, -1, v193
	v_cmp_gt_i32_e64 s[16:17], s45, v193
	s_and_b64 s[22:23], vcc, s[16:17]
	v_add_f32_e32 v215, v32, v215
	v_cndmask_b32_e64 v63, v254, v215, s[22:23]
	v_add_f32_e32 v216, v33, v216
	v_cndmask_b32_e64 v62, v254, v216, s[22:23]
	v_add_f32_e32 v217, v34, v217
	v_cndmask_b32_e64 v98, v254, v217, s[22:23]
	ds_read_b32 v213, v117 offset:980
	ds_read_b32 v214, v117 offset:984
	ds_read_b32 v215, v117 offset:988
	ds_read_b32 v216, v117 offset:1024
	ds_read_b32 v217, v117 offset:1028
	s_waitcnt lgkmcnt(10)
	v_add_f32_e32 v218, v35, v218
	v_cndmask_b32_e64 v32, v254, v218, s[22:23]
	v_add_f32_e32 v219, v36, v219
	v_cndmask_b32_e64 v176, v254, v219, s[22:23]
	v_add_f32_e32 v220, v37, v220
	v_cndmask_b32_e64 v99, v254, v220, s[22:23]
	v_add_f32_e32 v221, v38, v221
	v_cndmask_b32_e64 v37, v254, v221, s[22:23]
	v_add_f32_e32 v222, v39, v222
	v_cndmask_b32_e64 v36, v254, v222, s[22:23]
	ds_read_b32 v218, v117 offset:1032
	ds_read_b32 v219, v117 offset:1036
	ds_read_b32 v220, v117 offset:1040
	ds_read_b32 v221, v117 offset:1044
	ds_read_b32 v222, v117 offset:1048
	s_movk_i32 s16, 0xffef
	v_cmp_lt_i32_e32 vcc, s16, v193
	v_cmp_gt_i32_e64 s[16:17], s51, v193
	s_and_b64 s[20:21], vcc, s[16:17]
	s_waitcnt lgkmcnt(10)
	v_add_f32_e32 v223, v40, v223
	v_cndmask_b32_e64 v39, v254, v223, s[20:21]
	v_add_f32_e32 v224, v41, v224
	v_cndmask_b32_e64 v38, v254, v224, s[20:21]
	v_add_f32_e32 v225, v42, v225
	v_cndmask_b32_e64 v41, v254, v225, s[20:21]
	v_add_f32_e32 v226, v43, v226
	v_cndmask_b32_e64 v40, v254, v226, s[20:21]
	v_add_f32_e32 v227, v44, v227
	v_cndmask_b32_e64 v43, v254, v227, s[20:21]
	ds_read_b32 v223, v117 offset:1052
	ds_read_b32 v224, v117 offset:1088
	ds_read_b32 v225, v117 offset:1092
	ds_read_b32 v226, v117 offset:1096
	ds_read_b32 v227, v117 offset:1100
	s_waitcnt lgkmcnt(10)
	v_add_f32_e32 v213, v45, v213
	v_cndmask_b32_e64 v42, v254, v213, s[20:21]
	v_add_f32_e32 v214, v46, v214
	v_cndmask_b32_e64 v45, v254, v214, s[20:21]
	v_add_f32_e32 v215, v47, v215
	v_cndmask_b32_e64 v44, v254, v215, s[20:21]
	s_movk_i32 s16, 0xffdf
	v_cmp_lt_i32_e32 vcc, s16, v193
	v_cmp_gt_i32_e64 s[16:17], s52, v193
	s_and_b64 s[16:17], vcc, s[16:17]
	v_add_f32_e32 v216, v16, v216
	v_cndmask_b32_e64 v47, v254, v216, s[16:17]
	v_add_f32_e32 v217, v17, v217
	v_cndmask_b32_e64 v46, v254, v217, s[16:17]
	ds_read_b32 v213, v117 offset:1104
	ds_read_b32 v214, v117 offset:1108
	ds_read_b32 v215, v117 offset:1112
	ds_read_b32 v216, v117 offset:1116
	ds_read_b32 v217, v117 offset:1152
	s_waitcnt lgkmcnt(10)
	v_add_f32_e32 v218, v18, v218
	v_cndmask_b32_e64 v17, v254, v218, s[16:17]
	v_add_f32_e32 v219, v19, v219
	v_cndmask_b32_e64 v16, v254, v219, s[16:17]
	v_add_f32_e32 v220, v20, v220
	v_cndmask_b32_e64 v19, v254, v220, s[16:17]
	v_add_f32_e32 v221, v21, v221
	v_cndmask_b32_e64 v18, v254, v221, s[16:17]
	v_add_f32_e32 v222, v22, v222
	v_cndmask_b32_e64 v21, v254, v222, s[16:17]
	ds_read_b32 v218, v117 offset:1156
	ds_read_b32 v219, v117 offset:1160
	ds_read_b32 v220, v117 offset:1164
	ds_read_b32 v221, v117 offset:1168
	ds_read_b32 v222, v117 offset:1172
	s_waitcnt lgkmcnt(10)
	v_add_f32_e32 v223, v23, v223
	v_cndmask_b32_e64 v20, v254, v223, s[16:17]
	s_movk_i32 s24, 0xffcf
	v_cmp_lt_i32_e32 vcc, s24, v193
	v_cmp_gt_i32_e64 s[24:25], s53, v193
	s_and_b64 s[24:25], vcc, s[24:25]
	v_add_f32_e32 v224, v24, v224
	v_cndmask_b32_e64 v23, v254, v224, s[24:25]
	v_add_f32_e32 v225, v25, v225
	v_cndmask_b32_e64 v22, v254, v225, s[24:25]
	v_add_f32_e32 v226, v26, v226
	v_cndmask_b32_e64 v25, v254, v226, s[24:25]
	v_add_f32_e32 v227, v27, v227
	v_cndmask_b32_e64 v24, v254, v227, s[24:25]
	ds_read_b32 v223, v117 offset:1176
	ds_read_b32 v224, v117 offset:1180
	ds_read_b32 v225, v117 offset:1216
	ds_read_b32 v226, v117 offset:1220
	ds_read_b32 v227, v117 offset:1224
	s_waitcnt lgkmcnt(10)
	v_add_f32_e32 v213, v28, v213
	v_cndmask_b32_e64 v27, v254, v213, s[24:25]
	v_add_f32_e32 v214, v29, v214
	v_cndmask_b32_e64 v26, v254, v214, s[24:25]
	v_add_f32_e32 v215, v30, v215
	v_cndmask_b32_e64 v29, v254, v215, s[24:25]
	v_add_f32_e32 v216, v31, v216
	v_cndmask_b32_e64 v28, v254, v216, s[24:25]
	s_movk_i32 s26, 0xffbf
	v_cmp_lt_i32_e32 vcc, s26, v193
	v_cmp_gt_i32_e64 s[26:27], s54, v193
	s_and_b64 s[26:27], vcc, s[26:27]
	s_and_b64 s[34:35], s[26:27], s[76:77]
	v_add_f32_e32 v217, v0, v217
	v_cndmask_b32_e64 v31, v254, v217, s[34:35]
	ds_read_b32 v213, v117 offset:1228
	ds_read_b32 v214, v117 offset:1232
	ds_read_b32 v215, v117 offset:1236
	ds_read_b32 v216, v117 offset:1240
	ds_read_b32 v217, v117 offset:1244
	s_and_b64 s[34:35], s[26:27], s[78:79]
	s_waitcnt lgkmcnt(10)
	v_add_f32_e32 v218, v1, v218
	v_cndmask_b32_e64 v30, v254, v218, s[34:35]
	s_and_b64 s[34:35], s[26:27], s[80:81]
	v_add_f32_e32 v219, v2, v219
	v_cndmask_b32_e64 v235, v254, v219, s[34:35]
	s_and_b64 s[34:35], s[26:27], s[82:83]
	v_add_f32_e32 v220, v3, v220
	v_cndmask_b32_e64 v1, v254, v220, s[34:35]
	s_and_b64 s[34:35], s[26:27], s[84:85]
	v_add_f32_e32 v221, v4, v221
	v_cndmask_b32_e64 v3, v254, v221, s[34:35]
	s_and_b64 s[34:35], s[26:27], s[86:87]
	v_add_f32_e32 v222, v5, v222
	v_cndmask_b32_e64 v2, v254, v222, s[34:35]
	s_and_b64 s[34:35], s[26:27], s[88:89]
	s_waitcnt lgkmcnt(5)
	v_add_f32_e32 v223, v6, v223
	v_cndmask_b32_e64 v5, v254, v223, s[34:35]
	s_and_b64 s[34:35], s[26:27], s[90:91]
	v_add_f32_e32 v224, v7, v224
	v_cndmask_b32_e64 v4, v254, v224, s[34:35]
	s_movk_i32 s30, 0xffaf
	v_cmp_lt_i32_e32 vcc, s30, v193
	v_cmp_gt_i32_e64 s[30:31], s55, v193
	s_and_b64 s[30:31], vcc, s[30:31]
	s_and_b64 vcc, s[30:31], s[92:93]
	v_add_f32_e32 v225, v8, v225
	v_cndmask_b32_e32 v7, v254, v225, vcc
	s_and_b64 vcc, s[30:31], s[94:95]
	v_add_f32_e32 v226, v9, v226
	v_cndmask_b32_e32 v6, v254, v226, vcc
	s_and_b64 vcc, s[30:31], s[96:97]
	v_add_f32_e32 v227, v10, v227
	v_cndmask_b32_e32 v9, v254, v227, vcc
	s_and_b64 vcc, s[30:31], s[4:5]
	s_waitcnt lgkmcnt(0)
	v_add_f32_e32 v213, v11, v213
	v_cndmask_b32_e32 v8, v254, v213, vcc
	s_and_b64 vcc, s[30:31], s[6:7]
	v_add_f32_e32 v214, v12, v214
	v_cndmask_b32_e32 v11, v254, v214, vcc
	s_and_b64 vcc, s[30:31], s[8:9]
	v_add_f32_e32 v215, v13, v215
	v_cndmask_b32_e32 v10, v254, v215, vcc
	s_and_b64 vcc, s[30:31], s[10:11]
	v_add_f32_e32 v216, v14, v216
	v_cndmask_b32_e32 v13, v254, v216, vcc
	s_and_b64 vcc, s[30:31], s[12:13]
	v_add_f32_e32 v217, v15, v217
	v_cndmask_b32_e32 v12, v254, v217, vcc
	v_add_u32_e32 v0, v193, v103
	v_lshl_add_u32 v33, v0, s44, v194
	v_cndmask_b32_e64 v15, 0, 1, s[42:43]
	v_add_u32_e32 v34, s40, v33
	v_mov_b32_e32 v0, 0
	v_mov_b32_e32 v14, 0xf149f2ca
	v_cmp_ne_u32_e64 s[34:35], 1, v15
	s_andn2_b64 vcc, exec, s[42:43]
	v_mov_b32_e32 v233, 0
	s_cbranch_vccnz .LBB0_274
	v_lshl_add_u32 v14, v34, 2, 0
	v_add_u32_e32 v15, 0x22000, v14
	v_add_u32_e32 v35, 0x22800, v14
	ds_read_b32 v14, v15
	ds_read_b32 v233, v35
